# seam: tight poll (s_sleep removed from both arrival-counter spin loops)
# baseline (speedup 1.0000x reference)
.LBB0_823:
	s_and_b32 s1, s0, 0xff
	s_mov_b64 s[20:21], -1
	s_cmp_lg_u32 s1, 0
	s_mov_b64 s[26:27], -1
	s_nop 0
	s_cbranch_scc0 .LBB0_826
	s_and_b64 vcc, exec, s[26:27]
	s_cbranch_vccz .LBB0_822
